# top-k block selection (P2 prompt tasks and P3 sample task): extraction loop rewritten branch-free (max below ceiling via wrapped-subtract min3 tree, tie count via xor/min/add3) - removes all VCC cmp/c
# speedup vs baseline: 1.0318x; 1.0053x over previous
; __device__ __forceinline__ int dpp_x1(int x) { return __builtin_amdgcn_update_dpp(0, x, 0xB1, 0xF, 0xF, true); }
; __device__ __forceinline__ int dpp_x2(int x) { return __builtin_amdgcn_update_dpp(0, x, 0x4E, 0xF, 0xF, true); }
; __device__ __forceinline__ int quad_isum(int v) { v += dpp_x1(v); v += dpp_x2(v); return v; }
; __device__ __forceinline__ int half_isum(int v) { auto rr = __builtin_amdgcn_permlane32_swap((unsigned)v, (unsigned)v, false, false); return (int)(rr[0] + rr[1]); }
; __device__ __forceinline__ void cmp_task_lds(const Prm& P, Ctx& C, int b, int kvh, int tg, CStream& CS, const LAS bf16_t* wlb, const int NGW, bf16x8 (&qnx)[4], int& qnx_tg, const int tg_next) {
;     ...
;             for (int it = 0; it < 15; ++it) {
;                 unsigned t[16];
; #pragma unroll
;                 for (int e = 0; e < 16; ++e) t[e] = v[e] < ceil_ ? v[e] : 0u;
; #pragma unroll
;                 for (int st = 8; st >= 1; st >>= 1)
; #pragma unroll
;                     for (int e = 0; e < st; ++e) t[e] = t[e] > t[e + st] ? t[e] : t[e + st];
;                 unsigned mx = t[0];
;                 { const unsigned o1 = (unsigned)dpp_x1((int)mx); mx = mx > o1 ? mx : o1; const unsigned o2 = (unsigned)dpp_x2((int)mx); mx = mx > o2 ? mx : o2;
;                   auto rr = __builtin_amdgcn_permlane32_swap(mx, mx, false, false); mx = rr[0] > rr[1] ? rr[0] : rr[1]; }
;                 int c4[4] = {0, 0, 0, 0};
; #pragma unroll
;                 for (int e = 0; e < 16; ++e) c4[e & 3] += (v[e] == mx) ? 1 : 0;
;                 const int c = half_isum(quad_isum((c4[0] + c4[1]) + (c4[2] + c4[3])));
;                 if (!done) { taken += c; if (taken >= kk) { prefix = mx; done = true; } else ceil_ = mx; }
.LBB0_1105:
	s_xor_b64 s[58:59], s[56:57], -1
	s_or_b64 s[54:55], s[54:55], exec
	v_add_u32_e32 v45, -1, v21
	v_sub_u32_e32 v37, v45, v28
	v_sub_u32_e32 v38, v45, v26
	v_sub_u32_e32 v39, v45, v25
	v_sub_u32_e32 v40, v45, v7
	v_sub_u32_e32 v41, v45, v8
	v_sub_u32_e32 v42, v45, v5
	v_min3_u32 v37, v37, v38, v39
	v_sub_u32_e32 v38, v45, v6
	v_sub_u32_e32 v39, v45, v22
	v_sub_u32_e32 v43, v45, v27
	v_min3_u32 v40, v40, v41, v42
	v_sub_u32_e32 v41, v45, v35
	v_sub_u32_e32 v42, v45, v34
	v_sub_u32_e32 v44, v45, v33
	v_min3_u32 v38, v38, v39, v43
	v_sub_u32_e32 v39, v45, v32
	v_sub_u32_e32 v43, v45, v31
	v_min3_u32 v41, v41, v42, v44
	v_sub_u32_e32 v42, v45, v30
	v_sub_u32_e32 v44, v45, v29
	v_min3_u32 v39, v39, v43, v42
	v_min3_u32 v37, v37, v40, v38
	v_min3_u32 v39, v41, v39, v44
	v_min_u32_e32 v37, v37, v39
	s_nop 1
	v_min_u32_dpp v37, v37, v37 quad_perm:[1,0,3,2] row_mask:0xf bank_mask:0xf bound_ctrl:1
	s_nop 1
	v_min_u32_dpp v37, v37, v37 quad_perm:[2,3,0,1] row_mask:0xf bank_mask:0xf bound_ctrl:1
	v_mov_b32_e32 v38, v37
	s_nop 1
	v_permlane32_swap_b32_e32 v37, v38
	v_min_u32_e32 v37, v37, v38
	v_sub_u32_e32 v37, v45, v37
	v_xor_b32_e32 v38, v28, v37
	v_xor_b32_e32 v39, v26, v37
	v_xor_b32_e32 v40, v25, v37
	v_min_u32_e32 v38, 1, v38
	v_min_u32_e32 v39, 1, v39
	v_min_u32_e32 v40, 1, v40
	v_add3_u32 v38, v38, v39, v40
	v_xor_b32_e32 v39, v7, v37
	v_xor_b32_e32 v40, v8, v37
	v_min_u32_e32 v39, 1, v39
	v_min_u32_e32 v40, 1, v40
	v_add3_u32 v38, v38, v39, v40
	v_xor_b32_e32 v41, v5, v37
	v_xor_b32_e32 v42, v6, v37
	v_min_u32_e32 v41, 1, v41
	v_min_u32_e32 v42, 1, v42
	v_add3_u32 v38, v38, v41, v42
	v_xor_b32_e32 v39, v22, v37
	v_xor_b32_e32 v40, v27, v37
	v_min_u32_e32 v39, 1, v39
	v_min_u32_e32 v40, 1, v40
	v_add3_u32 v38, v38, v39, v40
	v_xor_b32_e32 v41, v35, v37
	v_xor_b32_e32 v42, v34, v37
	v_min_u32_e32 v41, 1, v41
	v_min_u32_e32 v42, 1, v42
	v_add3_u32 v38, v38, v41, v42
	v_xor_b32_e32 v39, v33, v37
	v_xor_b32_e32 v40, v32, v37
	v_min_u32_e32 v39, 1, v39
	v_min_u32_e32 v40, 1, v40
	v_add3_u32 v38, v38, v39, v40
	v_xor_b32_e32 v41, v31, v37
	v_xor_b32_e32 v42, v30, v37
	v_min_u32_e32 v41, 1, v41
	v_min_u32_e32 v42, 1, v42
	v_add3_u32 v38, v38, v41, v42
	v_xor_b32_e32 v39, v29, v37
	v_min_u32_e32 v39, 1, v39
	v_add_u32_e32 v38, v38, v39
	v_sub_u32_e32 v38, 16, v38
	s_nop 1
	v_add_u32_dpp v38, v38, v38 quad_perm:[1,0,3,2] row_mask:0xf bank_mask:0xf bound_ctrl:1
	s_nop 1
	v_add_u32_dpp v38, v38, v38 quad_perm:[2,3,0,1] row_mask:0xf bank_mask:0xf bound_ctrl:1
	v_mov_b32_e32 v39, v38
	s_nop 1
	v_permlane32_swap_b32_e32 v38, v39
	s_and_saveexec_b64 s[60:61], s[58:59]
	s_cbranch_execz .LBB0_1104
	v_add3_u32 v24, v39, v24, v38
	v_cmp_le_i32_e32 vcc, s76, v24
	s_andn2_b64 s[40:41], s[54:55], exec
	s_and_b64 s[54:55], vcc, exec
	v_cndmask_b32_e32 v23, v23, v37, vcc
	v_cndmask_b32_e32 v21, v37, v21, vcc
	s_or_b64 s[54:55], s[40:41], s[54:55]
	s_branch .LBB0_1104

; __device__ __forceinline__ int dpp_x1(int x) { return __builtin_amdgcn_update_dpp(0, x, 0xB1, 0xF, 0xF, true); }
; __device__ __forceinline__ int dpp_x2(int x) { return __builtin_amdgcn_update_dpp(0, x, 0x4E, 0xF, 0xF, true); }
; __device__ __forceinline__ int quad_isum(int v) { v += dpp_x1(v); v += dpp_x2(v); return v; }
; template <int NBL>
; __device__ __forceinline__ unsigned topk_select(const LAS float* sc  , int sub, int cur) {
;     ...
;         for (int it = 0; it < 15; ++it) {
;             unsigned t[NBL];
; #pragma unroll
;             for (int e = 0; e < NBL; ++e) t[e] = v[e] < ceil_ ? v[e] : 0u;
; #pragma unroll
;             for (int st = NBL / 2; st >= 1; st >>= 1)
; #pragma unroll
;                 for (int e = 0; e < st; ++e) t[e] = t[e] > t[e + st] ? t[e] : t[e + st];
;             unsigned mx = t[0];
;             { const unsigned o1 = (unsigned)dpp_x1((int)mx); mx = mx > o1 ? mx : o1; const unsigned o2 = (unsigned)dpp_x2((int)mx); mx = mx > o2 ? mx : o2;
;               const unsigned o3 = (unsigned)__builtin_amdgcn_update_dpp(0, (int)mx, 0x141, 0xF, 0xF, true); mx = mx > o3 ? mx : o3; }
;             int c4[4] = {0, 0, 0, 0};
; #pragma unroll
;             for (int e = 0; e < NBL; ++e) c4[e & 3] += (v[e] == mx) ? 1 : 0;
;             int c = quad_isum((c4[0] + c4[1]) + (c4[2] + c4[3])); c += __builtin_amdgcn_update_dpp(0, c, 0x141, 0xF, 0xF, true);
;             if (!done) { taken += c; if (taken >= kk) { prefix = mx; done = true; } else ceil_ = mx; }
.LBB0_1535:
	s_xor_b64 s[4:5], s[2:3], -1
	s_or_b64 s[0:1], s[0:1], exec
	s_waitcnt lgkmcnt(0)
	v_add_u32_e32 v54, -1, v35
	v_sub_u32_e32 v42, v54, v34
	v_sub_u32_e32 v43, v54, v30
	v_sub_u32_e32 v44, v54, v31
	v_sub_u32_e32 v45, v54, v28
	v_min_u32_e32 v38, v42, v43
	v_sub_u32_e32 v46, v54, v29
	v_sub_u32_e32 v47, v54, v26
	v_min_u32_e32 v39, v44, v45
	v_sub_u32_e32 v48, v54, v27
	v_sub_u32_e32 v49, v54, v24
	v_min_u32_e32 v40, v46, v47
	v_sub_u32_e32 v42, v54, v25
	v_sub_u32_e32 v43, v54, v22
	v_min_u32_e32 v41, v48, v49
	v_sub_u32_e32 v44, v54, v23
	v_sub_u32_e32 v45, v54, v20
	v_min3_u32 v38, v38, v42, v43
	v_sub_u32_e32 v46, v54, v21
	v_sub_u32_e32 v47, v54, v18
	v_min3_u32 v39, v39, v44, v45
	v_sub_u32_e32 v48, v54, v19
	v_sub_u32_e32 v49, v54, v16
	v_min3_u32 v40, v40, v46, v47
	v_sub_u32_e32 v42, v54, v17
	v_sub_u32_e32 v43, v54, v14
	v_min3_u32 v41, v41, v48, v49
	v_sub_u32_e32 v44, v54, v15
	v_sub_u32_e32 v45, v54, v12
	v_min3_u32 v38, v38, v42, v43
	v_sub_u32_e32 v46, v54, v13
	v_sub_u32_e32 v47, v54, v10
	v_min3_u32 v39, v39, v44, v45
	v_sub_u32_e32 v48, v54, v11
	v_sub_u32_e32 v49, v54, v8
	v_min3_u32 v40, v40, v46, v47
	v_sub_u32_e32 v42, v54, v9
	v_sub_u32_e32 v43, v54, v6
	v_min3_u32 v41, v41, v48, v49
	v_sub_u32_e32 v44, v54, v7
	v_sub_u32_e32 v45, v54, v4
	v_min3_u32 v38, v38, v42, v43
	v_sub_u32_e32 v46, v54, v5
	v_sub_u32_e32 v47, v54, v2
	v_min3_u32 v39, v39, v44, v45
	v_sub_u32_e32 v48, v54, v3
	v_sub_u32_e32 v49, v54, v0
	v_min3_u32 v40, v40, v46, v47
	v_min3_u32 v41, v41, v48, v49
	v_min3_u32 v38, v38, v39, v40
	v_min_u32_e32 v38, v38, v41
	s_nop 1
	v_min_u32_dpp v38, v38, v38 quad_perm:[1,0,3,2] row_mask:0xf bank_mask:0xf bound_ctrl:1
	s_nop 1
	v_min_u32_dpp v38, v38, v38 quad_perm:[2,3,0,1] row_mask:0xf bank_mask:0xf bound_ctrl:1
	s_nop 1
	v_min_u32_dpp v38, v38, v38 row_half_mirror row_mask:0xf bank_mask:0xf bound_ctrl:1
	v_sub_u32_e32 v38, v54, v38
	v_xor_b32_e32 v41, v34, v38
	v_xor_b32_e32 v42, v30, v38
	v_min_u32_e32 v41, 1, v41
	v_min_u32_e32 v42, 1, v42
	v_xor_b32_e32 v43, v31, v38
	v_xor_b32_e32 v44, v28, v38
	v_min_u32_e32 v43, 1, v43
	v_min_u32_e32 v44, 1, v44
	v_add_u32_e32 v39, v41, v42
	v_xor_b32_e32 v45, v29, v38
	v_xor_b32_e32 v46, v26, v38
	v_min_u32_e32 v45, 1, v45
	v_min_u32_e32 v46, 1, v46
	v_add_u32_e32 v40, v43, v44
	v_xor_b32_e32 v47, v27, v38
	v_xor_b32_e32 v48, v24, v38
	v_min_u32_e32 v47, 1, v47
	v_min_u32_e32 v48, 1, v48
	v_add3_u32 v39, v39, v45, v46
	v_xor_b32_e32 v41, v25, v38
	v_xor_b32_e32 v42, v22, v38
	v_min_u32_e32 v41, 1, v41
	v_min_u32_e32 v42, 1, v42
	v_add3_u32 v40, v40, v47, v48
	v_xor_b32_e32 v43, v23, v38
	v_xor_b32_e32 v44, v20, v38
	v_min_u32_e32 v43, 1, v43
	v_min_u32_e32 v44, 1, v44
	v_add3_u32 v39, v39, v41, v42
	v_xor_b32_e32 v45, v21, v38
	v_xor_b32_e32 v46, v18, v38
	v_min_u32_e32 v45, 1, v45
	v_min_u32_e32 v46, 1, v46
	v_add3_u32 v40, v40, v43, v44
	v_xor_b32_e32 v47, v19, v38
	v_xor_b32_e32 v48, v16, v38
	v_min_u32_e32 v47, 1, v47
	v_min_u32_e32 v48, 1, v48
	v_add3_u32 v39, v39, v45, v46
	v_xor_b32_e32 v41, v17, v38
	v_xor_b32_e32 v42, v14, v38
	v_min_u32_e32 v41, 1, v41
	v_min_u32_e32 v42, 1, v42
	v_add3_u32 v40, v40, v47, v48
	v_xor_b32_e32 v43, v15, v38
	v_xor_b32_e32 v44, v12, v38
	v_min_u32_e32 v43, 1, v43
	v_min_u32_e32 v44, 1, v44
	v_add3_u32 v39, v39, v41, v42
	v_xor_b32_e32 v45, v13, v38
	v_xor_b32_e32 v46, v10, v38
	v_min_u32_e32 v45, 1, v45
	v_min_u32_e32 v46, 1, v46
	v_add3_u32 v40, v40, v43, v44
	v_xor_b32_e32 v47, v11, v38
	v_xor_b32_e32 v48, v8, v38
	v_min_u32_e32 v47, 1, v47
	v_min_u32_e32 v48, 1, v48
	v_add3_u32 v39, v39, v45, v46
	v_xor_b32_e32 v41, v9, v38
	v_xor_b32_e32 v42, v6, v38
	v_min_u32_e32 v41, 1, v41
	v_min_u32_e32 v42, 1, v42
	v_add3_u32 v40, v40, v47, v48
	v_xor_b32_e32 v43, v7, v38
	v_xor_b32_e32 v44, v4, v38
	v_min_u32_e32 v43, 1, v43
	v_min_u32_e32 v44, 1, v44
	v_add3_u32 v39, v39, v41, v42
	v_xor_b32_e32 v45, v5, v38
	v_xor_b32_e32 v46, v2, v38
	v_min_u32_e32 v45, 1, v45
	v_min_u32_e32 v46, 1, v46
	v_add3_u32 v40, v40, v43, v44
	v_xor_b32_e32 v47, v3, v38
	v_xor_b32_e32 v48, v0, v38
	v_min_u32_e32 v47, 1, v47
	v_min_u32_e32 v48, 1, v48
	v_add3_u32 v39, v39, v45, v46
	v_add3_u32 v40, v40, v47, v48
	v_add_u32_e32 v39, v39, v40
	v_sub_u32_e32 v39, 32, v39
	s_nop 1
	v_add_u32_dpp v39, v39, v39 quad_perm:[1,0,3,2] row_mask:0xf bank_mask:0xf bound_ctrl:1
	s_nop 1
	v_add_u32_dpp v39, v39, v39 quad_perm:[2,3,0,1] row_mask:0xf bank_mask:0xf bound_ctrl:1
	s_nop 1
	v_mov_b32_dpp v40, v39 row_half_mirror row_mask:0xf bank_mask:0xf bound_ctrl:1
	s_and_saveexec_b64 s[6:7], s[4:5]
	s_cbranch_execz .LBB0_1534
	v_add3_u32 v37, v40, v37, v39
	v_cmp_lt_i32_e32 vcc, 12, v37
	s_andn2_b64 s[0:1], s[0:1], exec
	s_and_b64 s[2:3], vcc, exec
	v_cndmask_b32_e32 v35, v38, v35, vcc
	v_cndmask_b32_e32 v33, v33, v38, vcc
	s_or_b64 s[0:1], s[0:1], s[2:3]
	s_branch .LBB0_1534
